# G1 in-projection epilogue: the eight per-row stat loads issued together up front (one wait) instead of a load-wait per row group
# speedup vs baseline: 1.0197x; 1.0032x over previous
; __device__ __forceinline__ unsigned pkbf(float lo, float hi) { f2_t v = {lo, hi}; return __builtin_bit_cast(unsigned, __builtin_convertvector(v, bf2_t)); }
; __device__ __forceinline__ float bflo(unsigned w) { return __uint_as_float(w << 16); }
; __device__ __forceinline__ float bfhi(unsigned w) { return __uint_as_float(w & 0xffff0000u); }
;     __device__ __forceinline__ void operator()(const f32x4 (&acc)[2][2][4][2], const Unit& u, int wr, int wc, int fr, int fq) const {
;     ...
;             for (int m = 0; m < 4; ++m) { const int row = row0 + ai * HALF + m * 16; const float sc = rsqrtf(ss[row] * invk + eps);
;                 if (pn < 4) { float h[8];
; #pragma unroll
;                     for (int n = 0; n < 2; ++n)
; #pragma unroll
;                         for (int j = 0; j < 4; ++j) h[4 * n + j] = (acc[ai][0][m][n][j] * sc) * (acc[ai][1][m][n][j] * sc);
;                     u32x4 w; w.x = pkbf(h[0], h[1]); w.y = pkbf(h[2], h[3]); w.z = pkbf(h[4], h[5]); w.w = pkbf(h[6], h[7]);
;                     *(u32x4*)(ub + (size_t)row * 512 + pn * HALF + cw) = w;
;     ...
;                         const int c = bj * HALF + cw;
;                         if (pn < 6) *(u32x4*)(gbb + (size_t)row * 512 + (pn - 4) * BM + c) = w;
;                         else if (pn < 9) { *(u32x4*)(Aq + (size_t)row * 768 + (pn - 6) * BM + c) = w;
;                             const float a0 = bflo(w.x), a1 = bfhi(w.x), a2 = bflo(w.y), a3 = bfhi(w.y), a4 = bflo(w.z), a5 = bfhi(w.z), a6 = bflo(w.w), a7 = bfhi(w.w);
;                             ssum += (a0 * a0 + a1 * a1) + (a2 * a2 + a3 * a3) + (a4 * a4 + a5 * a5) + (a6 * a6 + a7 * a7); }
;                         else if (pn == 9) *(u32x4*)(zs + (size_t)row * 320 + c) = w;
;                         else if (c < 32) *(u32x4*)(zs + (size_t)row * 320 + 256 + c) = w; }
.LBB0_178:
	v_lshl_add_u32 v158, s46, 8, v149
	v_ashrrev_i32_e32 v159, 31, v158
	v_lshl_add_u64 v[160:161], v[158:159], 2, s[18:19]
	global_load_dword v204, v[160:161], off
	global_load_dword v205, v[160:161], off offset:64
	global_load_dword v206, v[160:161], off offset:128
	global_load_dword v207, v[160:161], off offset:192
	global_load_dword v208, v[160:161], off offset:512
	global_load_dword v209, v[160:161], off offset:576
	global_load_dword v210, v[160:161], off offset:640
	global_load_dword v211, v[160:161], off offset:704
	s_cmp_gt_i32 s44, 3
	s_cselect_b64 s[96:97], -1, 0
	s_cmp_gt_i32 s44, 5
	s_cselect_b64 s[68:69], -1, 0
	s_cmp_gt_u32 s44, 8
	s_cselect_b64 s[64:65], -1, 0
	s_cmp_eq_u32 s44, 9
	s_cselect_b64 s[58:59], -1, 0
	s_cmp_lg_u32 s44, 9
	s_cselect_b64 s[62:63], -1, 0
	s_lshl_b32 s10, s44, 8
	s_add_i32 s60, s10, 0xfffffc00
	s_add_i32 s0, s44, -6
	s_cmp_lt_u32 s0, 3
	s_cselect_b64 s[56:57], -1, 0
	s_cmp_lt_i32 s44, 4
	s_mov_b32 s61, s11
	s_mov_b64 s[46:47], -1
	v_lshlrev_b64 v[164:165], 10, v[158:159]
	s_waitcnt vmcnt(0)
	v_fmamk_f32 v128, v204, 0x3a800000, v134
	v_cmp_gt_f32_e32 vcc, s13, v128
	v_mul_f32_e32 v129, 0x4b800000, v128
	s_nop 0
	v_cndmask_b32_e32 v128, v128, v129, vcc
	v_rsq_f32_e32 v128, v128
	s_nop 0
	v_mul_f32_e32 v129, 0x45800000, v128
	v_cndmask_b32_e32 v162, v128, v129, vcc
	s_cbranch_scc1 .LBB0_208
	v_pk_mul_f32 v[130:131], v[126:127], v[162:163] op_sel_hi:[1,0]
	v_pk_mul_f32 v[128:129], v[124:125], v[162:163] op_sel_hi:[1,0]
	v_pk_mul_f32 v[170:171], v[122:123], v[162:163] op_sel_hi:[1,0]
	v_pk_mul_f32 v[194:195], v[120:121], v[162:163] op_sel_hi:[1,0]
	v_mad_i64_i32 v[168:169], s[0:1], v158, s79, 0
	v_mad_i64_i32 v[166:167], s[0:1], v158, s78, 0
	v_cvt_pk_bf16_f32 v128, v128, v129
	v_cvt_pk_bf16_f32 v129, v130, v131
	v_cvt_pk_bf16_f32 v130, v194, v195
	v_cvt_pk_bf16_f32 v131, v170, v171
	s_and_b64 vcc, exec, s[68:69]
	s_cbranch_vccz .LBB0_191
	s_and_b64 vcc, exec, s[64:65]
	s_cbranch_vccz .LBB0_188
	s_and_b64 vcc, exec, s[62:63]
	s_cbranch_vccz .LBB0_185
	s_andn2_b64 vcc, exec, s[20:21]
	s_cbranch_vccnz .LBB0_184
	v_lshl_add_u64 v[170:171], v[150:151], 0, v[168:169]
	global_store_dwordx4 v[170:171], v[128:131], off offset:512

;     __device__ __forceinline__ void operator()(const f32x4 (&acc)[2][2][4][2], const Unit& u, int wr, int wc, int fr, int fq) const {
;     ...
;             for (int m = 0; m < 4; ++m) { const int row = row0 + ai * HALF + m * 16; const float sc = rsqrtf(ss[row] * invk + eps);
.LBB0_210:
	v_or_b32_e32 v120, 16, v158
	v_ashrrev_i32_e32 v121, 31, v120
	v_lshl_add_u64 v[112:113], v[120:121], 2, s[18:19]
	s_nop 1
	s_mov_b64 s[70:71], -1
	v_lshlrev_b64 v[118:119], 10, v[120:121]
	v_fmamk_f32 v112, v205, 0x3a800000, v134
	v_cmp_gt_f32_e32 vcc, s13, v112
	v_mul_f32_e32 v113, 0x4b800000, v112
	s_nop 0
	v_cndmask_b32_e32 v112, v112, v113, vcc
	v_rsq_f32_e32 v112, v112
	s_nop 0
	v_mul_f32_e32 v113, 0x45800000, v112
	v_cndmask_b32_e32 v116, v112, v113, vcc
	v_cndmask_b32_e64 v112, 0, 1, s[96:97]
	v_cmp_ne_u32_e64 s[46:47], 1, v112
	v_cndmask_b32_e64 v112, 0, 1, s[68:69]
	s_andn2_b64 vcc, exec, s[96:97]
	v_cmp_ne_u32_e64 s[44:45], 1, v112
	s_cbranch_vccnz .LBB0_240
	v_pk_mul_f32 v[114:115], v[110:111], v[116:117] op_sel_hi:[1,0]
	v_pk_mul_f32 v[112:113], v[108:109], v[116:117] op_sel_hi:[1,0]
	v_pk_mul_f32 v[126:127], v[106:107], v[116:117] op_sel_hi:[1,0]
	s_waitcnt lgkmcnt(0)
	v_pk_mul_f32 v[128:129], v[104:105], v[116:117] op_sel_hi:[1,0]
	v_mad_i64_i32 v[124:125], s[0:1], v120, s79, 0
	v_mad_i64_i32 v[122:123], s[0:1], v120, s78, 0
	v_cvt_pk_bf16_f32 v112, v112, v113
	v_cvt_pk_bf16_f32 v113, v114, v115
	v_cvt_pk_bf16_f32 v114, v128, v129
	v_cvt_pk_bf16_f32 v115, v126, v127
	s_and_b64 vcc, exec, s[44:45]
	s_mov_b64 s[68:69], -1
	s_cbranch_vccnz .LBB0_223
	s_andn2_b64 vcc, exec, s[64:65]
	s_cbranch_vccnz .LBB0_220
	s_andn2_b64 vcc, exec, s[62:63]
	s_cbranch_vccnz .LBB0_217
	s_andn2_b64 vcc, exec, s[20:21]
	s_cbranch_vccnz .LBB0_216
	v_lshl_add_u64 v[126:127], v[150:151], 0, v[124:125]
	global_store_dwordx4 v[126:127], v[112:115], off offset:512

;     __device__ __forceinline__ void operator()(const f32x4 (&acc)[2][2][4][2], const Unit& u, int wr, int wc, int fr, int fq) const {
;     ...
;             for (int m = 0; m < 4; ++m) { const int row = row0 + ai * HALF + m * 16; const float sc = rsqrtf(ss[row] * invk + eps);
.LBB0_242:
	v_or_b32_e32 v104, 32, v158
	v_ashrrev_i32_e32 v105, 31, v104
	v_lshl_add_u64 v[96:97], v[104:105], 2, s[18:19]
	s_nop 1
	s_mov_b64 s[68:69], -1
	v_lshlrev_b64 v[102:103], 10, v[104:105]
	v_fmamk_f32 v96, v206, 0x3a800000, v134
	v_cmp_gt_f32_e32 vcc, s13, v96
	v_mul_f32_e32 v97, 0x4b800000, v96
	s_nop 0
	v_cndmask_b32_e32 v96, v96, v97, vcc
	v_rsq_f32_e32 v96, v96
	s_nop 0
	v_mul_f32_e32 v97, 0x45800000, v96
	v_cndmask_b32_e32 v100, v96, v97, vcc
	s_and_b64 vcc, exec, s[46:47]
	s_cbranch_vccnz .LBB0_272
	v_pk_mul_f32 v[98:99], v[94:95], v[100:101] op_sel_hi:[1,0]
	v_pk_mul_f32 v[96:97], v[92:93], v[100:101] op_sel_hi:[1,0]
	v_pk_mul_f32 v[110:111], v[90:91], v[100:101] op_sel_hi:[1,0]
	s_waitcnt lgkmcnt(0)
	v_pk_mul_f32 v[112:113], v[88:89], v[100:101] op_sel_hi:[1,0]
	v_mad_i64_i32 v[108:109], s[0:1], v104, s79, 0
	v_mad_i64_i32 v[106:107], s[0:1], v104, s78, 0
	v_cvt_pk_bf16_f32 v96, v96, v97
	v_cvt_pk_bf16_f32 v97, v98, v99
	v_cvt_pk_bf16_f32 v98, v112, v113
	v_cvt_pk_bf16_f32 v99, v110, v111
	s_and_b64 vcc, exec, s[44:45]
	s_cbranch_vccnz .LBB0_255
	s_andn2_b64 vcc, exec, s[64:65]
	s_cbranch_vccnz .LBB0_252
	s_andn2_b64 vcc, exec, s[62:63]
	s_cbranch_vccnz .LBB0_249
	s_andn2_b64 vcc, exec, s[20:21]
	s_cbranch_vccnz .LBB0_248
	v_lshl_add_u64 v[110:111], v[150:151], 0, v[108:109]
	global_store_dwordx4 v[110:111], v[96:99], off offset:512

;     __device__ __forceinline__ void operator()(const f32x4 (&acc)[2][2][4][2], const Unit& u, int wr, int wc, int fr, int fq) const {
;     ...
;             for (int m = 0; m < 4; ++m) { const int row = row0 + ai * HALF + m * 16; const float sc = rsqrtf(ss[row] * invk + eps);
.LBB0_274:
	v_or_b32_e32 v88, 48, v158
	v_ashrrev_i32_e32 v89, 31, v88
	v_lshl_add_u64 v[80:81], v[88:89], 2, s[18:19]
	s_nop 1
	s_mov_b64 s[68:69], -1
	v_lshlrev_b64 v[86:87], 10, v[88:89]
	v_fmamk_f32 v80, v207, 0x3a800000, v134
	v_cmp_gt_f32_e32 vcc, s13, v80
	v_mul_f32_e32 v81, 0x4b800000, v80
	s_nop 0
	v_cndmask_b32_e32 v80, v80, v81, vcc
	v_rsq_f32_e32 v80, v80
	s_nop 0
	v_mul_f32_e32 v81, 0x45800000, v80
	v_cndmask_b32_e32 v84, v80, v81, vcc
	s_and_b64 vcc, exec, s[46:47]
	s_cbranch_vccnz .LBB0_304
	v_pk_mul_f32 v[82:83], v[78:79], v[84:85] op_sel_hi:[1,0]
	v_pk_mul_f32 v[80:81], v[76:77], v[84:85] op_sel_hi:[1,0]
	v_pk_mul_f32 v[94:95], v[74:75], v[84:85] op_sel_hi:[1,0]
	s_waitcnt lgkmcnt(0)
	v_pk_mul_f32 v[96:97], v[72:73], v[84:85] op_sel_hi:[1,0]
	v_mad_i64_i32 v[92:93], s[0:1], v88, s79, 0
	v_mad_i64_i32 v[90:91], s[0:1], v88, s78, 0
	v_cvt_pk_bf16_f32 v80, v80, v81
	v_cvt_pk_bf16_f32 v81, v82, v83
	v_cvt_pk_bf16_f32 v82, v96, v97
	v_cvt_pk_bf16_f32 v83, v94, v95
	s_and_b64 vcc, exec, s[44:45]
	s_cbranch_vccnz .LBB0_287
	s_andn2_b64 vcc, exec, s[64:65]
	s_cbranch_vccnz .LBB0_284
	s_andn2_b64 vcc, exec, s[62:63]
	s_cbranch_vccnz .LBB0_281
	s_andn2_b64 vcc, exec, s[20:21]
	s_cbranch_vccnz .LBB0_280
	v_lshl_add_u64 v[94:95], v[150:151], 0, v[92:93]
	global_store_dwordx4 v[94:95], v[80:83], off offset:512

;     __device__ __forceinline__ void operator()(const f32x4 (&acc)[2][2][4][2], const Unit& u, int wr, int wc, int fr, int fq) const {
;     ...
;             for (int m = 0; m < 4; ++m) { const int row = row0 + ai * HALF + m * 16; const float sc = rsqrtf(ss[row] * invk + eps);
.LBB0_306:
	s_nop 1
	v_add_u32_e32 v70, 0x80, v158
	v_ashrrev_i32_e32 v71, 31, v70
	s_mov_b64 s[68:69], -1
	v_lshlrev_b64 v[72:73], 10, v[70:71]
	v_fmamk_f32 v64, v208, 0x3a800000, v134
	v_cmp_gt_f32_e32 vcc, s13, v64
	v_mul_f32_e32 v65, 0x4b800000, v64
	s_nop 0
	v_cndmask_b32_e32 v64, v64, v65, vcc
	v_rsq_f32_e32 v64, v64
	s_nop 0
	v_mul_f32_e32 v65, 0x45800000, v64
	v_cndmask_b32_e32 v68, v64, v65, vcc
	s_and_b64 vcc, exec, s[46:47]
	s_cbranch_vccnz .LBB0_336
	v_pk_mul_f32 v[66:67], v[62:63], v[68:69] op_sel_hi:[1,0]
	v_pk_mul_f32 v[64:65], v[60:61], v[68:69] op_sel_hi:[1,0]
	v_pk_mul_f32 v[78:79], v[58:59], v[68:69] op_sel_hi:[1,0]
	s_waitcnt lgkmcnt(0)
	v_pk_mul_f32 v[80:81], v[56:57], v[68:69] op_sel_hi:[1,0]
	v_mad_i64_i32 v[76:77], s[0:1], v70, s79, 0
	v_mad_i64_i32 v[74:75], s[0:1], v70, s78, 0
	v_cvt_pk_bf16_f32 v64, v64, v65
	v_cvt_pk_bf16_f32 v65, v66, v67
	v_cvt_pk_bf16_f32 v66, v80, v81
	v_cvt_pk_bf16_f32 v67, v78, v79
	s_and_b64 vcc, exec, s[44:45]
	s_cbranch_vccnz .LBB0_319
	s_andn2_b64 vcc, exec, s[64:65]
	s_cbranch_vccnz .LBB0_316
	s_andn2_b64 vcc, exec, s[62:63]
	s_cbranch_vccnz .LBB0_313
	s_andn2_b64 vcc, exec, s[20:21]
	s_cbranch_vccnz .LBB0_312
	v_lshl_add_u64 v[78:79], v[150:151], 0, v[76:77]
	global_store_dwordx4 v[78:79], v[64:67], off offset:512

; __device__ __forceinline__ unsigned pkbf(float lo, float hi) { f2_t v = {lo, hi}; return __builtin_bit_cast(unsigned, __builtin_convertvector(v, bf2_t)); }
;     __device__ __forceinline__ void operator()(const f32x4 (&acc)[2][2][4][2], const Unit& u, int wr, int wc, int fr, int fq) const {
;     ...
;             for (int m = 0; m < 4; ++m) { const int row = row0 + ai * HALF + m * 16; const float sc = rsqrtf(ss[row] * invk + eps);
;                 if (pn < 4) { float h[8];
; #pragma unroll
;                     for (int n = 0; n < 2; ++n)
; #pragma unroll
;                         for (int j = 0; j < 4; ++j) h[4 * n + j] = (acc[ai][0][m][n][j] * sc) * (acc[ai][1][m][n][j] * sc);
;                     u32x4 w; w.x = pkbf(h[0], h[1]); w.y = pkbf(h[2], h[3]); w.z = pkbf(h[4], h[5]); w.w = pkbf(h[6], h[7]);
;                     *(u32x4*)(ub + (size_t)row * 512 + pn * HALF + cw) = w;
;                 } else { float ssum = 0.f;
; #pragma unroll
;                     for (int bj = 0; bj < 2; ++bj) { const f32x4 v0 = acc[ai][bj][m][0] * sc, v1 = acc[ai][bj][m][1] * sc;
;                         u32x4 w; w.x = pkbf(v0[0], v0[1]); w.y = pkbf(v0[2], v0[3]); w.z = pkbf(v1[0], v1[1]); w.w = pkbf(v1[2], v1[3]);
;                         const int c = bj * HALF + cw;
;                         if (pn < 6) *(u32x4*)(gbb + (size_t)row * 512 + (pn - 4) * BM + c) = w;
.LBB0_338:
	s_nop 1
	v_add_u32_e32 v54, 0x90, v158
	v_ashrrev_i32_e32 v55, 31, v54
	s_mov_b64 s[68:69], -1
	v_lshlrev_b64 v[56:57], 10, v[54:55]
	v_fmamk_f32 v48, v209, 0x3a800000, v134
	v_cmp_gt_f32_e32 vcc, s13, v48
	v_mul_f32_e32 v49, 0x4b800000, v48
	s_nop 0
	v_cndmask_b32_e32 v48, v48, v49, vcc
	v_rsq_f32_e32 v48, v48
	s_nop 0
	v_mul_f32_e32 v49, 0x45800000, v48
	v_cndmask_b32_e32 v52, v48, v49, vcc
	s_and_b64 vcc, exec, s[46:47]
	s_cbranch_vccnz .LBB0_368
	v_pk_mul_f32 v[50:51], v[46:47], v[52:53] op_sel_hi:[1,0]
	v_pk_mul_f32 v[48:49], v[44:45], v[52:53] op_sel_hi:[1,0]
	v_pk_mul_f32 v[62:63], v[42:43], v[52:53] op_sel_hi:[1,0]
	s_waitcnt lgkmcnt(0)
	v_pk_mul_f32 v[64:65], v[40:41], v[52:53] op_sel_hi:[1,0]
	v_mad_i64_i32 v[60:61], s[0:1], v54, s79, 0
	v_mad_i64_i32 v[58:59], s[0:1], v54, s78, 0
	v_cvt_pk_bf16_f32 v48, v48, v49
	v_cvt_pk_bf16_f32 v49, v50, v51
	v_cvt_pk_bf16_f32 v50, v64, v65
	v_cvt_pk_bf16_f32 v51, v62, v63
	s_and_b64 vcc, exec, s[44:45]
	s_cbranch_vccnz .LBB0_351
	s_andn2_b64 vcc, exec, s[64:65]
	s_cbranch_vccnz .LBB0_348
	s_andn2_b64 vcc, exec, s[62:63]
	s_cbranch_vccnz .LBB0_345
	s_andn2_b64 vcc, exec, s[20:21]
	s_cbranch_vccnz .LBB0_344
	v_lshl_add_u64 v[62:63], v[150:151], 0, v[60:61]
	global_store_dwordx4 v[62:63], v[48:51], off offset:512

; __device__ __forceinline__ unsigned pkbf(float lo, float hi) { f2_t v = {lo, hi}; return __builtin_bit_cast(unsigned, __builtin_convertvector(v, bf2_t)); }
;     __device__ __forceinline__ void operator()(const f32x4 (&acc)[2][2][4][2], const Unit& u, int wr, int wc, int fr, int fq) const {
;     ...
;             for (int m = 0; m < 4; ++m) { const int row = row0 + ai * HALF + m * 16; const float sc = rsqrtf(ss[row] * invk + eps);
;                 if (pn < 4) { float h[8];
; #pragma unroll
;                     for (int n = 0; n < 2; ++n)
; #pragma unroll
;                         for (int j = 0; j < 4; ++j) h[4 * n + j] = (acc[ai][0][m][n][j] * sc) * (acc[ai][1][m][n][j] * sc);
;                     u32x4 w; w.x = pkbf(h[0], h[1]); w.y = pkbf(h[2], h[3]); w.z = pkbf(h[4], h[5]); w.w = pkbf(h[6], h[7]);
;                     *(u32x4*)(ub + (size_t)row * 512 + pn * HALF + cw) = w;
;                 } else { float ssum = 0.f;
; #pragma unroll
;                     for (int bj = 0; bj < 2; ++bj) { const f32x4 v0 = acc[ai][bj][m][0] * sc, v1 = acc[ai][bj][m][1] * sc;
;                         u32x4 w; w.x = pkbf(v0[0], v0[1]); w.y = pkbf(v0[2], v0[3]); w.z = pkbf(v1[0], v1[1]); w.w = pkbf(v1[2], v1[3]);
;                         const int c = bj * HALF + cw;
;                         if (pn < 6) *(u32x4*)(gbb + (size_t)row * 512 + (pn - 4) * BM + c) = w;
.LBB0_370:
	s_nop 1
	v_add_u32_e32 v38, 0xa0, v158
	v_ashrrev_i32_e32 v39, 31, v38
	s_mov_b64 s[68:69], -1
	v_lshlrev_b64 v[40:41], 10, v[38:39]
	v_fmamk_f32 v32, v210, 0x3a800000, v134
	v_cmp_gt_f32_e32 vcc, s13, v32
	v_mul_f32_e32 v33, 0x4b800000, v32
	s_nop 0
	v_cndmask_b32_e32 v32, v32, v33, vcc
	v_rsq_f32_e32 v32, v32
	s_nop 0
	v_mul_f32_e32 v33, 0x45800000, v32
	v_cndmask_b32_e32 v36, v32, v33, vcc
	s_and_b64 vcc, exec, s[46:47]
	s_cbranch_vccnz .LBB0_400
	v_pk_mul_f32 v[34:35], v[30:31], v[36:37] op_sel_hi:[1,0]
	v_pk_mul_f32 v[32:33], v[28:29], v[36:37] op_sel_hi:[1,0]
	v_pk_mul_f32 v[46:47], v[26:27], v[36:37] op_sel_hi:[1,0]
	s_waitcnt lgkmcnt(0)
	v_pk_mul_f32 v[48:49], v[24:25], v[36:37] op_sel_hi:[1,0]
	v_mad_i64_i32 v[44:45], s[0:1], v38, s79, 0
	v_mad_i64_i32 v[42:43], s[0:1], v38, s78, 0
	v_cvt_pk_bf16_f32 v32, v32, v33
	v_cvt_pk_bf16_f32 v33, v34, v35
	v_cvt_pk_bf16_f32 v34, v48, v49
	v_cvt_pk_bf16_f32 v35, v46, v47
	s_and_b64 vcc, exec, s[44:45]
	s_cbranch_vccnz .LBB0_383
	s_andn2_b64 vcc, exec, s[64:65]
	s_cbranch_vccnz .LBB0_380
	s_andn2_b64 vcc, exec, s[62:63]
	s_cbranch_vccnz .LBB0_377
	s_andn2_b64 vcc, exec, s[20:21]
	s_cbranch_vccnz .LBB0_376
	v_lshl_add_u64 v[46:47], v[150:151], 0, v[44:45]
	global_store_dwordx4 v[46:47], v[32:35], off offset:512

; __device__ __forceinline__ unsigned pkbf(float lo, float hi) { f2_t v = {lo, hi}; return __builtin_bit_cast(unsigned, __builtin_convertvector(v, bf2_t)); }
;     __device__ __forceinline__ void operator()(const f32x4 (&acc)[2][2][4][2], const Unit& u, int wr, int wc, int fr, int fq) const {
;     ...
;             for (int m = 0; m < 4; ++m) { const int row = row0 + ai * HALF + m * 16; const float sc = rsqrtf(ss[row] * invk + eps);
;                 if (pn < 4) { float h[8];
; #pragma unroll
;                     for (int n = 0; n < 2; ++n)
; #pragma unroll
;                         for (int j = 0; j < 4; ++j) h[4 * n + j] = (acc[ai][0][m][n][j] * sc) * (acc[ai][1][m][n][j] * sc);
;                     u32x4 w; w.x = pkbf(h[0], h[1]); w.y = pkbf(h[2], h[3]); w.z = pkbf(h[4], h[5]); w.w = pkbf(h[6], h[7]);
;                     *(u32x4*)(ub + (size_t)row * 512 + pn * HALF + cw) = w;
;                 } else { float ssum = 0.f;
; #pragma unroll
;                     for (int bj = 0; bj < 2; ++bj) { const f32x4 v0 = acc[ai][bj][m][0] * sc, v1 = acc[ai][bj][m][1] * sc;
;                         u32x4 w; w.x = pkbf(v0[0], v0[1]); w.y = pkbf(v0[2], v0[3]); w.z = pkbf(v1[0], v1[1]); w.w = pkbf(v1[2], v1[3]);
;                         const int c = bj * HALF + cw;
;                         if (pn < 6) *(u32x4*)(gbb + (size_t)row * 512 + (pn - 4) * BM + c) = w;
.LBB0_402:
	s_nop 1
	v_add_u32_e32 v22, 0xb0, v158
	v_ashrrev_i32_e32 v23, 31, v22
	s_mov_b64 s[68:69], -1
	v_lshlrev_b64 v[24:25], 10, v[22:23]
	v_fmamk_f32 v16, v211, 0x3a800000, v134
	v_cmp_gt_f32_e32 vcc, s13, v16
	v_mul_f32_e32 v17, 0x4b800000, v16
	s_nop 0
	v_cndmask_b32_e32 v16, v16, v17, vcc
	v_rsq_f32_e32 v16, v16
	s_nop 0
	v_mul_f32_e32 v17, 0x45800000, v16
	v_cndmask_b32_e32 v20, v16, v17, vcc
	s_and_b64 vcc, exec, s[46:47]
	s_cbranch_vccnz .LBB0_429
	v_pk_mul_f32 v[18:19], v[14:15], v[20:21] op_sel_hi:[1,0]
	v_pk_mul_f32 v[16:17], v[12:13], v[20:21] op_sel_hi:[1,0]
	v_pk_mul_f32 v[30:31], v[10:11], v[20:21] op_sel_hi:[1,0]
	s_waitcnt lgkmcnt(0)
	v_pk_mul_f32 v[32:33], v[8:9], v[20:21] op_sel_hi:[1,0]
	v_cndmask_b32_e64 v21, 0, 1, s[64:65]
	v_mad_i64_i32 v[28:29], s[0:1], v22, s79, 0
	v_mad_i64_i32 v[26:27], s[0:1], v22, s78, 0
	v_cvt_pk_bf16_f32 v16, v16, v17
	v_cvt_pk_bf16_f32 v17, v18, v19
	v_cvt_pk_bf16_f32 v18, v32, v33
	v_cvt_pk_bf16_f32 v19, v30, v31
	s_and_b64 vcc, exec, s[44:45]
	v_cmp_ne_u32_e64 s[46:47], 1, v21
	s_cbranch_vccnz .LBB0_415
	s_and_b64 vcc, exec, s[46:47]
	s_mov_b64 s[64:65], -1
	s_cbranch_vccnz .LBB0_412
	s_andn2_b64 vcc, exec, s[62:63]
	s_mov_b64 s[62:63], -1
	s_cbranch_vccnz .LBB0_409
	s_andn2_b64 vcc, exec, s[20:21]
	s_cbranch_vccnz .LBB0_408
	v_lshl_add_u64 v[30:31], v[150:151], 0, v[28:29]
	global_store_dwordx4 v[30:31], v[16:19], off offset:512
